# ret_prompt score section software-pipelined (double-buffered K fragments) on top of G2 in-register gated merge
# speedup vs baseline: 1.0271x; 1.0035x over previous
; #define LAS __attribute__((address_space(3)))
; __device__ __forceinline__ unsigned cvt_pk(float lo, float hi) { const f32x2 v = {lo, hi}; const bf16x2_t b = __builtin_convertvector(v, bf16x2_t); return __builtin_bit_cast(unsigned, b); }
; __device__ __forceinline__ float bflo(unsigned u) { return __uint_as_float(u << 16); }
; __device__ __forceinline__ void mix_ret_prompt(const Params& p, LAS unsigned char* lds, int u) {
;     ...
;     __syncthreads();
; #pragma unroll
;     for (int it = 0; it < 4; ++it) {
;       const int ch = tid + it * 512, row = ch >> 4, cc = ch & 15;
;       *(LAS u32x4*)(Qi + row * 272 + cc * 16) = nq[it];
;       *(LAS u32x4*)(Ki + row * 272 + cc * 16) = nk[it];
;     }
; #pragma unroll
;     for (int it = 0; it < 2; ++it) {
;       const int ch = tid + it * 512, row = ch >> 3, cc = ch & 7;
;       const u32x4 vv = nv[it];
;       const float sc = __expf((float)(127 - row) * lg);
;       u32x4 o;
; #pragma unroll
;       for (int e = 0; e < 4; ++e) o[e] = cvt_pk(bflo(vv[e]) * sc, bfhi(vv[e]) * sc);
;       *(LAS u32x4*)(Vi + row * 144 + cc * 16) = o;
;     }
; #pragma unroll
;     for (int n = 0; n < 4; ++n) *(LAS u32x2*)(Si + irow * 144 + (16 * n + 4 * fq) * 2) = pack4(accS[n]);
;     if (c + 1 < 16) {
;       const int t1 = t0 + 128;
; #pragma unroll
;       for (int it = 0; it < 4; ++it) {
;         const int ch = tid + it * 512, row = ch >> 4, cc = ch & 15;
;         nq[it] = *(const u32x4*)(RQ + (size_t)(t1 + row) * 1024 + h * 128 + cc * 8);
;         nk[it] = *(const u32x4*)(RK + (size_t)(t1 + row) * 1024 + h * 128 + cc * 8);
;       }
; #pragma unroll
;       for (int it = 0; it < 2; ++it) {
;         const int ch = tid + it * 512, row = ch >> 3, cc = ch & 7;
;         nv[it] = *(const u32x4*)(RV + (size_t)(t1 + row) * 2048 + h * 256 + es * 64 + cc * 8);
;       }
;     }
;     __syncthreads();
;     bf16x8 Qf[4];
; #pragma unroll
;     for (int ks = 0; ks < 4; ++ks) Qf[ks] = ldfrag(Qi, irow, 32 * ks + 8 * fq, 272);
;     f32x4 sc8[8];
; #pragma unroll
;     for (int nt = 0; nt < 8; ++nt) {
;       sc8[nt] = (f32x4){0.f, 0.f, 0.f, 0.f};
; #pragma unroll
;       for (int ks = 0; ks < 4; ++ks) sc8[nt] = MFMA16(ldfrag(Ki, 16 * nt + fr, 32 * ks + 8 * fq, 272), Qf[ks], sc8[nt]);
; #pragma unroll
;       for (int j = 0; j < 4; ++j) if (16 * nt + 4 * fq + j > irow) sc8[nt][j] = 0.f;
;     }
.LBB0_243:
	s_barrier
	s_waitcnt vmcnt(0)
	ds_write_b128 v225, v[16:19]
	s_waitcnt vmcnt(8)
	ds_write_b128 v225, v[20:23] offset:34816
	s_waitcnt vmcnt(7)
	ds_write_b128 v223, v[24:27]
	s_waitcnt vmcnt(6)
	ds_write_b128 v223, v[28:31] offset:34816
	s_waitcnt vmcnt(5)
	ds_write_b128 v221, v[36:39]
	s_waitcnt vmcnt(4)
	ds_write_b128 v221, v[40:43] offset:34816
	s_waitcnt vmcnt(3)
	ds_write_b128 v220, v[44:47]
	s_waitcnt vmcnt(2)
	ds_write_b128 v220, v[48:51] offset:34816
	s_waitcnt vmcnt(1)
	v_lshlrev_b32_e32 v16, 16, v52
	v_and_b32_e32 v17, 0xffff0000, v52
	v_lshlrev_b32_e32 v18, 16, v53
	v_and_b32_e32 v19, 0xffff0000, v53
	v_pk_mul_f32 v[16:17], v[182:183], v[16:17]
	v_pk_mul_f32 v[18:19], v[182:183], v[18:19]
	v_cvt_pk_bf16_f32 v16, v16, v17
	v_cvt_pk_bf16_f32 v17, v18, v19
	v_lshlrev_b32_e32 v18, 16, v54
	v_and_b32_e32 v19, 0xffff0000, v54
	v_lshlrev_b32_e32 v20, 16, v55
	v_and_b32_e32 v21, 0xffff0000, v55
	v_pk_mul_f32 v[18:19], v[182:183], v[18:19]
	v_pk_mul_f32 v[20:21], v[182:183], v[20:21]
	v_cvt_pk_bf16_f32 v18, v18, v19
	v_cvt_pk_bf16_f32 v19, v20, v21
	ds_write_b128 v211, v[16:19]
	s_waitcnt vmcnt(0)
	v_lshlrev_b32_e32 v16, 16, v32
	v_and_b32_e32 v17, 0xffff0000, v32
	v_add_u32_e32 v32, s35, v240
	v_lshlrev_b32_e32 v18, 16, v33
	v_and_b32_e32 v19, 0xffff0000, v33
	v_ashrrev_i32_e32 v33, 31, v32
	v_pk_mul_f32 v[16:17], v[180:181], v[16:17]
	v_pk_mul_f32 v[18:19], v[180:181], v[18:19]
	v_lshlrev_b64 v[32:33], 11, v[32:33]
	v_cvt_pk_bf16_f32 v16, v16, v17
	v_cvt_pk_bf16_f32 v17, v18, v19
	v_lshlrev_b32_e32 v18, 16, v34
	v_and_b32_e32 v19, 0xffff0000, v34
	v_lshlrev_b32_e32 v20, 16, v35
	v_and_b32_e32 v21, 0xffff0000, v35
	v_lshl_add_u64 v[34:35], v[174:175], 0, v[32:33]
	v_lshl_add_u64 v[32:33], v[176:177], 0, v[32:33]
	global_load_dwordx4 v[36:39], v[34:35], off
	global_load_dwordx4 v[40:43], v[32:33], off
	v_add_u32_e32 v32, s35, v239
	v_ashrrev_i32_e32 v33, 31, v32
	v_lshlrev_b64 v[32:33], 11, v[32:33]
	v_lshl_add_u64 v[34:35], v[174:175], 0, v[32:33]
	v_lshl_add_u64 v[32:33], v[176:177], 0, v[32:33]
	v_pk_mul_f32 v[18:19], v[180:181], v[18:19]
	v_pk_mul_f32 v[20:21], v[180:181], v[20:21]
	global_load_dwordx4 v[44:47], v[34:35], off
	global_load_dwordx4 v[48:51], v[32:33], off
	v_add_u32_e32 v32, s35, v238
	v_cvt_pk_bf16_f32 v18, v18, v19
	v_cvt_pk_bf16_f32 v19, v20, v21
	v_ashrrev_i32_e32 v33, 31, v32
	ds_write_b128 v210, v[16:19]
	v_cvt_pk_bf16_f32 v16, v12, v13
	v_cvt_pk_bf16_f32 v17, v14, v15
	v_cvt_pk_bf16_f32 v18, v4, v5
	v_cvt_pk_bf16_f32 v19, v6, v7
	v_lshlrev_b64 v[32:33], 12, v[32:33]
	ds_write2_b64 v209, v[16:17], v[18:19] offset1:4
	v_cvt_pk_bf16_f32 v16, v0, v1
	v_cvt_pk_bf16_f32 v17, v2, v3
	v_cvt_pk_bf16_f32 v18, v8, v9
	v_cvt_pk_bf16_f32 v19, v10, v11
	v_lshl_add_u64 v[32:33], v[178:179], 0, v[32:33]
	ds_write2_b64 v209, v[16:17], v[18:19] offset0:8 offset1:12
	v_add_u32_e32 v16, s35, v242
	v_add_u32_e32 v24, s35, v241
	global_load_dwordx4 v[52:55], v[32:33], off
	v_add_u32_e32 v32, s35, v224
	v_ashrrev_i32_e32 v17, 31, v16
	v_ashrrev_i32_e32 v25, 31, v24
	v_ashrrev_i32_e32 v33, 31, v32
	v_lshlrev_b64 v[20:21], 11, v[16:17]
	v_lshlrev_b64 v[28:29], 11, v[24:25]
	v_lshlrev_b64 v[32:33], 12, v[32:33]
	v_lshl_add_u64 v[16:17], v[174:175], 0, v[20:21]
	v_lshl_add_u64 v[20:21], v[176:177], 0, v[20:21]
	v_lshl_add_u64 v[24:25], v[174:175], 0, v[28:29]
	v_lshl_add_u64 v[28:29], v[176:177], 0, v[28:29]
	v_lshl_add_u64 v[32:33], v[178:179], 0, v[32:33]
	global_load_dwordx4 v[16:19], v[16:17], off
	v_add_u32_e32 v196, v213, v212
	global_load_dwordx4 v[20:23], v[20:21], off
	v_add_u32_e32 v197, v214, v212
	global_load_dwordx4 v[24:27], v[24:25], off
	v_add_u32_e32 v198, v215, v212
	global_load_dwordx4 v[28:31], v[28:29], off
	v_add_u32_e32 v199, v216, v212
	global_load_dwordx4 v[32:35], v[32:33], off
	s_waitcnt lgkmcnt(0)
	s_barrier
	ds_read_b128 v[134:137], v208
	ds_read_b128 v[130:133], v208 offset:64
	ds_read_b128 v[126:129], v208 offset:128
	ds_read_b128 v[122:125], v208 offset:192
	ds_read_b128 v[94:97], v195 offset:34816
	ds_read_b128 v[98:101], v195 offset:34880
	ds_read_b128 v[102:105], v195 offset:34944
	ds_read_b128 v[106:109], v195 offset:35008
	ds_read_b128 v[110:113], v195 offset:39168
	ds_read_b128 v[114:117], v195 offset:39232
	ds_read_b128 v[118:121], v195 offset:39296
	ds_read_b128 v[244:247], v195 offset:39360
	v_add_u32_e32 v200, v213, v217
	v_add_u32_e32 v201, v214, v217
	v_add_u32_e32 v202, v215, v217
	v_add_u32_e32 v203, v216, v217
	s_waitcnt lgkmcnt(4)
	v_mfma_f32_16x16x32_bf16 v[56:59], v[94:97], v[134:137], 0
	v_mfma_f32_16x16x32_bf16 v[56:59], v[98:101], v[130:133], v[56:59]
	v_mfma_f32_16x16x32_bf16 v[56:59], v[102:105], v[126:129], v[56:59]
	v_mfma_f32_16x16x32_bf16 v[56:59], v[106:109], v[122:125], v[56:59]
	ds_read_b128 v[94:97], v195 offset:43520
	ds_read_b128 v[98:101], v195 offset:43584
	ds_read_b128 v[102:105], v195 offset:43648
	ds_read_b128 v[106:109], v195 offset:43712
	v_add_u32_e32 v204, v213, v218
	v_add_u32_e32 v205, v214, v218
	v_add_u32_e32 v206, v215, v218
	v_add_u32_e32 v207, v216, v218
	v_cndmask_b32_e64 v60, v56, 0, s[92:93]
	v_cndmask_b32_e64 v66, v60, v56, s[90:91]
	v_cndmask_b32_e64 v67, 0, v57, s[90:91]
	v_cndmask_b32_e64 v68, v58, 0, s[94:95]
	v_cndmask_b32_e64 v69, v59, 0, s[96:97]
	s_waitcnt lgkmcnt(4)
; #define MFMA16(a, b, c) __builtin_amdgcn_mfma_f32_16x16x32_bf16((a), (b), (c), 0, 0, 0)
; __device__ __forceinline__ void mix_ret_prompt(const Params& p, LAS unsigned char* lds, int u) {
;     ...
;     f32x4 sc8[8];
; #pragma unroll
;     for (int nt = 0; nt < 8; ++nt) {
;       sc8[nt] = (f32x4){0.f, 0.f, 0.f, 0.f};
; #pragma unroll
;       for (int ks = 0; ks < 4; ++ks) sc8[nt] = MFMA16(ldfrag(Ki, 16 * nt + fr, 32 * ks + 8 * fq, 272), Qf[ks], sc8[nt]);
; #pragma unroll
;       for (int j = 0; j < 4; ++j) if (16 * nt + 4 * fq + j > irow) sc8[nt][j] = 0.f;
;     }
	v_mfma_f32_16x16x32_bf16 v[56:59], v[110:113], v[134:137], 0
	v_mfma_f32_16x16x32_bf16 v[56:59], v[114:117], v[130:133], v[56:59]
	v_mfma_f32_16x16x32_bf16 v[56:59], v[118:121], v[126:129], v[56:59]
	v_mfma_f32_16x16x32_bf16 v[56:59], v[244:247], v[122:125], v[56:59]
	ds_read_b128 v[110:113], v195 offset:47872
	ds_read_b128 v[114:117], v195 offset:47936
	ds_read_b128 v[118:121], v195 offset:48000
	ds_read_b128 v[244:247], v195 offset:48064
	v_cvt_pk_bf16_f32 v138, v66, v67
	v_cvt_pk_bf16_f32 v139, v68, v69
	v_add_u32_e32 v184, s35, v222
	v_ashrrev_i32_e32 v185, 31, v184
	v_lshlrev_b64 v[184:185], 12, v[184:185]
	v_lshl_add_u64 v[184:185], v[172:173], 0, v[184:185]
	v_cndmask_b32_e64 v70, v56, 0, s[82:83]
	v_cndmask_b32_e64 v71, v57, 0, s[84:85]
	v_cndmask_b32_e64 v72, v58, 0, s[86:87]
	v_cndmask_b32_e64 v73, v59, 0, s[88:89]
	s_waitcnt lgkmcnt(4)
	v_mfma_f32_16x16x32_bf16 v[56:59], v[94:97], v[134:137], 0
	v_mfma_f32_16x16x32_bf16 v[56:59], v[98:101], v[130:133], v[56:59]
	v_mfma_f32_16x16x32_bf16 v[56:59], v[102:105], v[126:129], v[56:59]
	v_mfma_f32_16x16x32_bf16 v[56:59], v[106:109], v[122:125], v[56:59]
	ds_read_b128 v[94:97], v195 offset:52224
	ds_read_b128 v[98:101], v195 offset:52288
	ds_read_b128 v[102:105], v195 offset:52352
	ds_read_b128 v[106:109], v195 offset:52416
	v_cvt_pk_bf16_f32 v140, v70, v71
	v_cvt_pk_bf16_f32 v141, v72, v73
	v_add_u32_e32 v243, v219, v212
	v_mov_b32_e32 v159, v158
	v_pk_mul_f32 v[14:15], v[158:159], v[14:15]
	v_pk_mul_f32 v[12:13], v[160:161], v[12:13]
	v_cndmask_b32_e64 v74, v56, 0, s[74:75]
	v_cndmask_b32_e64 v75, v57, 0, s[76:77]
	v_cndmask_b32_e64 v76, v58, 0, s[78:79]
	v_cndmask_b32_e64 v77, v59, 0, s[80:81]
	s_waitcnt lgkmcnt(4)
	v_mfma_f32_16x16x32_bf16 v[56:59], v[110:113], v[134:137], 0
	v_mfma_f32_16x16x32_bf16 v[56:59], v[114:117], v[130:133], v[56:59]
	v_mfma_f32_16x16x32_bf16 v[56:59], v[118:121], v[126:129], v[56:59]
	v_mfma_f32_16x16x32_bf16 v[56:59], v[244:247], v[122:125], v[56:59]
	ds_read_b128 v[110:113], v195 offset:56576
	ds_read_b128 v[114:117], v195 offset:56640
	ds_read_b128 v[118:121], v195 offset:56704
	ds_read_b128 v[244:247], v195 offset:56768
	v_cvt_pk_bf16_f32 v142, v74, v75
	v_cvt_pk_bf16_f32 v143, v76, v77
	v_pk_mul_f32 v[6:7], v[158:159], v[6:7]
	v_pk_mul_f32 v[4:5], v[160:161], v[4:5]
	v_pk_mul_f32 v[2:3], v[158:159], v[2:3]
	v_pk_mul_f32 v[0:1], v[160:161], v[0:1]
	v_cndmask_b32_e64 v78, v56, 0, s[66:67]
	v_cndmask_b32_e64 v79, v57, 0, s[68:69]
	v_cndmask_b32_e64 v80, v58, 0, s[70:71]
	v_cndmask_b32_e64 v81, v59, 0, s[72:73]
	s_waitcnt lgkmcnt(4)
	v_mfma_f32_16x16x32_bf16 v[56:59], v[94:97], v[134:137], 0
	v_mfma_f32_16x16x32_bf16 v[56:59], v[98:101], v[130:133], v[56:59]
	v_mfma_f32_16x16x32_bf16 v[56:59], v[102:105], v[126:129], v[56:59]
	v_mfma_f32_16x16x32_bf16 v[56:59], v[106:109], v[122:125], v[56:59]
	ds_read_b128 v[94:97], v195 offset:60928
	ds_read_b128 v[98:101], v195 offset:60992
	ds_read_b128 v[102:105], v195 offset:61056
	ds_read_b128 v[106:109], v195 offset:61120
	v_cvt_pk_bf16_f32 v144, v78, v79
	v_cvt_pk_bf16_f32 v145, v80, v81
	v_pk_mul_f32 v[10:11], v[158:159], v[10:11]
	v_pk_mul_f32 v[8:9], v[160:161], v[8:9]
	s_addk_i32 s35, 0x80
	s_cmpk_lg_i32 s35, 0x780
	v_cndmask_b32_e64 v82, v56, 0, s[58:59]
	v_cndmask_b32_e64 v83, v57, 0, s[60:61]
	v_cndmask_b32_e64 v84, v58, 0, s[62:63]
	v_cndmask_b32_e64 v85, v59, 0, s[64:65]
	s_waitcnt lgkmcnt(4)
	v_mfma_f32_16x16x32_bf16 v[56:59], v[110:113], v[134:137], 0
	v_mfma_f32_16x16x32_bf16 v[56:59], v[114:117], v[130:133], v[56:59]
	v_mfma_f32_16x16x32_bf16 v[56:59], v[118:121], v[126:129], v[56:59]
	v_mfma_f32_16x16x32_bf16 v[56:59], v[244:247], v[122:125], v[56:59]
	ds_read_b128 v[110:113], v195 offset:65280
	ds_read_b128 v[114:117], v195 offset:65344
	ds_read_b128 v[118:121], v195 offset:65408
	ds_read_b128 v[244:247], v195 offset:65472
	v_cvt_pk_bf16_f32 v146, v82, v83
	v_cvt_pk_bf16_f32 v147, v84, v85
	s_nop 0
	s_nop 0
	v_cndmask_b32_e64 v86, v56, 0, s[50:51]
	v_cndmask_b32_e64 v87, v57, 0, s[52:53]
	v_cndmask_b32_e64 v88, v58, 0, s[54:55]
	v_cndmask_b32_e64 v89, v59, 0, s[56:57]
	s_waitcnt lgkmcnt(4)
	v_mfma_f32_16x16x32_bf16 v[56:59], v[94:97], v[134:137], 0
	v_mfma_f32_16x16x32_bf16 v[56:59], v[98:101], v[130:133], v[56:59]
	v_mfma_f32_16x16x32_bf16 v[56:59], v[102:105], v[126:129], v[56:59]
	v_mfma_f32_16x16x32_bf16 v[56:59], v[106:109], v[122:125], v[56:59]
	v_cvt_pk_bf16_f32 v148, v86, v87
	v_cvt_pk_bf16_f32 v149, v88, v89
	s_nop 0
	s_nop 0
	s_nop 0
	s_nop 0
	s_nop 0
	s_nop 0
	v_cndmask_b32_e64 v90, v56, 0, s[42:43]
	v_cndmask_b32_e64 v91, v57, 0, s[44:45]
	v_cndmask_b32_e64 v92, v58, 0, s[46:47]
	v_cndmask_b32_e64 v93, v59, 0, s[48:49]
	s_waitcnt lgkmcnt(0)
; __device__ __forceinline__ u32x2 pack4(f32x4 v) { u32x2 r; r[0] = cvt_pk(v[0], v[1]); r[1] = cvt_pk(v[2], v[3]); return r; }
; #define MFMA16(a, b, c) __builtin_amdgcn_mfma_f32_16x16x32_bf16((a), (b), (c), 0, 0, 0)
; __device__ __forceinline__ void mix_ret_prompt(const Params& p, LAS unsigned char* lds, int u) {
;     ...
;     f32x4 sc8[8];
; #pragma unroll
;     for (int nt = 0; nt < 8; ++nt) {
;       sc8[nt] = (f32x4){0.f, 0.f, 0.f, 0.f};
; #pragma unroll
;       for (int ks = 0; ks < 4; ++ks) sc8[nt] = MFMA16(ldfrag(Ki, 16 * nt + fr, 32 * ks + 8 * fq, 272), Qf[ks], sc8[nt]);
; #pragma unroll
;       for (int j = 0; j < 4; ++j) if (16 * nt + 4 * fq + j > irow) sc8[nt][j] = 0.f;
;     }
;     bf16x8 Pf[4];
; #pragma unroll
;     for (int k2 = 0; k2 < 4; ++k2) {
;       const u32x2 lo = pack4(sc8[2 * k2]), hi = pack4(sc8[2 * k2 + 1]);
;       const u32x4 t = (u32x4){lo[0], lo[1], hi[0], hi[1]};
;       Pf[k2] = __builtin_bit_cast(bf16x8, t);
;     }
;     bf16x8 Vf[4][4];
; #pragma unroll
;     for (int n = 0; n < 4; ++n)
; #pragma unroll
;       for (int k2 = 0; k2 < 4; ++k2) Vf[n][k2] = ldfrag_tr(Vi, 32 * k2 + 4 * fq, 32 * k2 + 16 + 4 * fq, 16 * n, 144, lane);
; #pragma unroll
;     for (int n = 0; n < 4; ++n) {
;       f32x4 aA = (f32x4){0.f, 0.f, 0.f, 0.f}, aB = (f32x4){0.f, 0.f, 0.f, 0.f};
; #pragma unroll
;       for (int k2 = 0; k2 < 4; ++k2) aA = MFMA16(Vf[n][k2], Pf[k2], aA);
; #pragma unroll
;       for (int ks = 0; ks < 4; ++ks) aB = MFMA16(ldfrag_tr(Si, 32 * ks + 8 * fq, 32 * ks + 8 * fq + 4, 16 * n, 144, lane), Qf[ks], aB);
;       const f32x4 o = aA * sa + aB * sb;
;       *(u32x2*)(RO + (size_t)(t0 + irow) * 2048 + h * 256 + es * 64 + 16 * n + 4 * fq) = pack4(o);
;     }
	v_mfma_f32_16x16x32_bf16 v[56:59], v[110:113], v[134:137], 0
	v_mfma_f32_16x16x32_bf16 v[56:59], v[114:117], v[130:133], v[56:59]
	v_mfma_f32_16x16x32_bf16 v[56:59], v[118:121], v[126:129], v[56:59]
	v_mfma_f32_16x16x32_bf16 v[56:59], v[244:247], v[122:125], v[56:59]
	v_cvt_pk_bf16_f32 v150, v90, v91
	v_cvt_pk_bf16_f32 v151, v92, v93
	ds_read_b64_tr_b16 v[106:107], v194
	ds_read_b64_tr_b16 v[108:109], v194 offset:2304
	ds_read_b64_tr_b16 v[110:111], v193
	ds_read_b64_tr_b16 v[112:113], v193 offset:2304
	ds_read_b64_tr_b16 v[114:115], v192
	ds_read_b64_tr_b16 v[116:117], v192 offset:2304
	ds_read_b64_tr_b16 v[118:119], v191
	ds_read_b64_tr_b16 v[120:121], v191 offset:2304
	ds_read_b64_tr_b16 v[90:91], v196
	ds_read_b64_tr_b16 v[92:93], v196 offset:2304
	ds_read_b64_tr_b16 v[94:95], v197
	ds_read_b64_tr_b16 v[96:97], v197 offset:2304
	ds_read_b64_tr_b16 v[98:99], v198
	ds_read_b64_tr_b16 v[100:101], v198 offset:2304
	ds_read_b64_tr_b16 v[102:103], v199
	ds_read_b64_tr_b16 v[104:105], v199 offset:2304
	s_nop 1
	v_cndmask_b32_e64 v56, v56, 0, vcc
	v_cndmask_b32_e64 v57, v57, 0, s[36:37]
	v_cndmask_b32_e64 v58, v58, 0, s[38:39]
	v_cndmask_b32_e64 v59, v59, 0, s[40:41]
	v_cvt_pk_bf16_f32 v152, v56, v57
	v_cvt_pk_bf16_f32 v153, v58, v59
	ds_read_b64_tr_b16 v[74:75], v200
	ds_read_b64_tr_b16 v[76:77], v200 offset:2304
	ds_read_b64_tr_b16 v[78:79], v201
	ds_read_b64_tr_b16 v[80:81], v201 offset:2304
	ds_read_b64_tr_b16 v[82:83], v202
	ds_read_b64_tr_b16 v[84:85], v202 offset:2304
	ds_read_b64_tr_b16 v[86:87], v203
	ds_read_b64_tr_b16 v[88:89], v203 offset:2304
	ds_read_b64_tr_b16 v[70:71], v204
	ds_read_b64_tr_b16 v[72:73], v204 offset:2304
	ds_read_b64_tr_b16 v[66:67], v205
	ds_read_b64_tr_b16 v[68:69], v205 offset:2304
	ds_read_b64_tr_b16 v[60:61], v206
	ds_read_b64_tr_b16 v[62:63], v206 offset:2304
	ds_read_b64_tr_b16 v[56:57], v207
	ds_read_b64_tr_b16 v[58:59], v207 offset:2304
	ds_read_b64_tr_b16 v[244:245], v190
	ds_read_b64_tr_b16 v[246:247], v190 offset:576
	ds_read_b64_tr_b16 v[232:233], v190 offset:4608
	ds_read_b64_tr_b16 v[234:235], v190 offset:5184
	s_waitcnt lgkmcnt(2)
	v_mfma_f32_16x16x32_bf16 v[244:247], v[244:247], v[134:137], 0
	s_waitcnt lgkmcnt(0)
	v_mfma_f32_16x16x32_bf16 v[232:235], v[232:235], v[130:133], v[244:247]
	s_nop 5
	ds_read_b64_tr_b16 v[244:245], v190 offset:9216
	ds_read_b64_tr_b16 v[246:247], v190 offset:9792
	s_waitcnt lgkmcnt(0)
	v_mfma_f32_16x16x32_bf16 v[232:235], v[244:247], v[126:129], v[232:235]
	ds_read_b64_tr_b16 v[244:245], v190 offset:13824
	ds_read_b64_tr_b16 v[246:247], v190 offset:14400
	s_waitcnt lgkmcnt(0)
	v_mfma_f32_16x16x32_bf16 v[232:235], v[244:247], v[122:125], v[232:235]
	v_mfma_f32_16x16x32_bf16 v[244:247], v[106:109], v[138:141], 0
	v_mfma_f32_16x16x32_bf16 v[244:247], v[110:113], v[142:145], v[244:247]
	v_mfma_f32_16x16x32_bf16 v[244:247], v[114:117], v[146:149], v[244:247]
	v_mfma_f32_16x16x32_bf16 v[244:247], v[118:121], v[150:153], v[244:247]
	s_nop 7
	v_pk_mul_f32 v[246:247], v[166:167], v[246:247]
	v_pk_mul_f32 v[244:245], v[162:163], v[244:245]
	v_pk_fma_f32 v[234:235], v[170:171], v[234:235], v[246:247]
	v_pk_fma_f32 v[232:233], v[164:165], v[232:233], v[244:245]
	s_nop 0
	v_cvt_pk_bf16_f32 v232, v232, v233
	v_cvt_pk_bf16_f32 v233, v234, v235
	global_store_dwordx2 v[184:185], v[232:233], off
	ds_read_b64_tr_b16 v[232:233], v243
	ds_read_b64_tr_b16 v[234:235], v243 offset:576
	ds_read_b64_tr_b16 v[244:245], v189 offset:4608
	ds_read_b64_tr_b16 v[246:247], v189 offset:5184
	s_waitcnt lgkmcnt(2)
	v_mfma_f32_16x16x32_bf16 v[232:235], v[232:235], v[134:137], 0
	s_waitcnt lgkmcnt(0)
	v_mfma_f32_16x16x32_bf16 v[232:235], v[244:247], v[130:133], v[232:235]
	ds_read_b64_tr_b16 v[244:245], v189 offset:9216
	ds_read_b64_tr_b16 v[246:247], v189 offset:9792
	s_waitcnt lgkmcnt(0)
	v_mfma_f32_16x16x32_bf16 v[232:235], v[244:247], v[126:129], v[232:235]
	ds_read_b64_tr_b16 v[244:245], v189 offset:13824
	ds_read_b64_tr_b16 v[246:247], v189 offset:14400
	s_waitcnt lgkmcnt(0)
	v_mfma_f32_16x16x32_bf16 v[232:235], v[244:247], v[122:125], v[232:235]
	v_mfma_f32_16x16x32_bf16 v[244:247], v[90:93], v[138:141], 0
	v_mfma_f32_16x16x32_bf16 v[244:247], v[94:97], v[142:145], v[244:247]
	v_mfma_f32_16x16x32_bf16 v[244:247], v[98:101], v[146:149], v[244:247]
	v_mfma_f32_16x16x32_bf16 v[244:247], v[102:105], v[150:153], v[244:247]
	s_nop 7
	v_pk_mul_f32 v[246:247], v[166:167], v[246:247]
	v_pk_mul_f32 v[244:245], v[162:163], v[244:245]
	v_pk_fma_f32 v[234:235], v[170:171], v[234:235], v[246:247]
	v_pk_fma_f32 v[232:233], v[164:165], v[232:233], v[244:245]
	v_add_u32_e32 v244, v219, v217
	v_cvt_pk_bf16_f32 v232, v232, v233
	v_cvt_pk_bf16_f32 v233, v234, v235
	global_store_dwordx2 v[184:185], v[232:233], off offset:32
	ds_read_b64_tr_b16 v[232:233], v244
	ds_read_b64_tr_b16 v[234:235], v244 offset:576
	ds_read_b64_tr_b16 v[246:247], v188 offset:4608
	ds_read_b64_tr_b16 v[248:249], v188 offset:5184
	s_waitcnt lgkmcnt(2)
	v_mfma_f32_16x16x32_bf16 v[232:235], v[232:235], v[134:137], 0
	v_add_u32_e32 v245, v219, v218
	s_waitcnt lgkmcnt(0)
	v_mfma_f32_16x16x32_bf16 v[232:235], v[246:249], v[130:133], v[232:235]
	ds_read_b64_tr_b16 v[246:247], v188 offset:9216
	ds_read_b64_tr_b16 v[248:249], v188 offset:9792
	s_waitcnt lgkmcnt(0)
	v_mfma_f32_16x16x32_bf16 v[232:235], v[246:249], v[126:129], v[232:235]
	ds_read_b64_tr_b16 v[246:247], v188 offset:13824
	ds_read_b64_tr_b16 v[248:249], v188 offset:14400
	s_waitcnt lgkmcnt(0)
; #define LAS __attribute__((address_space(3)))
; __device__ __forceinline__ unsigned cvt_pk(float lo, float hi) { const f32x2 v = {lo, hi}; const bf16x2_t b = __builtin_convertvector(v, bf16x2_t); return __builtin_bit_cast(unsigned, b); }
; __device__ __forceinline__ float bflo(unsigned u) { return __uint_as_float(u << 16); }
; __device__ __forceinline__ float bfhi(unsigned u) { return __uint_as_float(u & 0xffff0000u); }
; __device__ __forceinline__ u32x2 pack4(f32x4 v) { u32x2 r; r[0] = cvt_pk(v[0], v[1]); r[1] = cvt_pk(v[2], v[3]); return r; }
; __device__ __forceinline__ void mix_ret_prompt(const Params& p, LAS unsigned char* lds, int u) {
;     ...
;     __syncthreads();
; #pragma unroll
;     for (int it = 0; it < 4; ++it) {
;       const int ch = tid + it * 512, row = ch >> 4, cc = ch & 15;
;       *(LAS u32x4*)(Qi + row * 272 + cc * 16) = nq[it];
;       *(LAS u32x4*)(Ki + row * 272 + cc * 16) = nk[it];
;     }
; #pragma unroll
;     for (int it = 0; it < 2; ++it) {
;       const int ch = tid + it * 512, row = ch >> 3, cc = ch & 7;
;       const u32x4 vv = nv[it];
;       const float sc = __expf((float)(127 - row) * lg);
;       u32x4 o;
; #pragma unroll
;       for (int e = 0; e < 4; ++e) o[e] = cvt_pk(bflo(vv[e]) * sc, bfhi(vv[e]) * sc);
;       *(LAS u32x4*)(Vi + row * 144 + cc * 16) = o;
;     }
; #pragma unroll
;     for (int n = 0; n < 4; ++n) *(LAS u32x2*)(Si + irow * 144 + (16 * n + 4 * fq) * 2) = pack4(accS[n]);
;     ...
;     for (int n = 0; n < 4; ++n) {
;       f32x4 aA = (f32x4){0.f, 0.f, 0.f, 0.f}, aB = (f32x4){0.f, 0.f, 0.f, 0.f};
; #pragma unroll
;       for (int k2 = 0; k2 < 4; ++k2) aA = MFMA16(Vf[n][k2], Pf[k2], aA);
; #pragma unroll
;       for (int ks = 0; ks < 4; ++ks) aB = MFMA16(ldfrag_tr(Si, 32 * ks + 8 * fq, 32 * ks + 8 * fq + 4, 16 * n, 144, lane), Qf[ks], aB);
;       const f32x4 o = aA * sa + aB * sb;
;       *(u32x2*)(RO + (size_t)(t0 + irow) * 2048 + h * 256 + es * 64 + 16 * n + 4 * fq) = pack4(o);
;     }
;     bf16x8 Kt[4];
; #pragma unroll
;     for (int k2 = 0; k2 < 4; ++k2) Kt[k2] = ldfrag_tr(Ki, 32 * k2 + 4 * fq, 32 * k2 + 16 + 4 * fq, 16 * w, 272, lane);
; #pragma unroll
;     for (int n = 0; n < 4; ++n) {
;       accS[n] = accS[n] * cd;
; #pragma unroll
;       for (int k2 = 0; k2 < 4; ++k2) accS[n] = MFMA16(Vf[n][k2], Kt[k2], accS[n]);
;     }
	v_mfma_f32_16x16x32_bf16 v[232:235], v[246:249], v[122:125], v[232:235]
	v_mfma_f32_16x16x32_bf16 v[246:249], v[74:77], v[138:141], 0
	v_mfma_f32_16x16x32_bf16 v[246:249], v[78:81], v[142:145], v[246:249]
	v_mfma_f32_16x16x32_bf16 v[246:249], v[82:85], v[146:149], v[246:249]
	v_mfma_f32_16x16x32_bf16 v[246:249], v[86:89], v[150:153], v[246:249]
	s_nop 7
	v_pk_mul_f32 v[248:249], v[166:167], v[248:249]
	v_pk_mul_f32 v[246:247], v[162:163], v[246:247]
	v_pk_fma_f32 v[234:235], v[170:171], v[234:235], v[248:249]
	v_pk_fma_f32 v[232:233], v[164:165], v[232:233], v[246:247]
	s_nop 0
	v_cvt_pk_bf16_f32 v232, v232, v233
	v_cvt_pk_bf16_f32 v233, v234, v235
	global_store_dwordx2 v[184:185], v[232:233], off offset:64
	ds_read_b64_tr_b16 v[232:233], v245
	ds_read_b64_tr_b16 v[234:235], v245 offset:576
	s_waitcnt lgkmcnt(0)
	v_mfma_f32_16x16x32_bf16 v[134:137], v[232:235], v[134:137], 0
	ds_read_b64_tr_b16 v[232:233], v187 offset:4608
	ds_read_b64_tr_b16 v[234:235], v187 offset:5184
	s_waitcnt lgkmcnt(0)
	v_mfma_f32_16x16x32_bf16 v[130:133], v[232:235], v[130:133], v[134:137]
	s_nop 3
	ds_read_b64_tr_b16 v[134:135], v187 offset:9216
	ds_read_b64_tr_b16 v[136:137], v187 offset:9792
	s_waitcnt lgkmcnt(0)
	v_mfma_f32_16x16x32_bf16 v[126:129], v[134:137], v[126:129], v[130:133]
	s_nop 2
	ds_read_b64_tr_b16 v[130:131], v187 offset:13824
	ds_read_b64_tr_b16 v[132:133], v187 offset:14400
	s_waitcnt lgkmcnt(0)
	v_mfma_f32_16x16x32_bf16 v[122:125], v[130:133], v[122:125], v[126:129]
	v_mfma_f32_16x16x32_bf16 v[126:129], v[70:73], v[138:141], 0
	v_mfma_f32_16x16x32_bf16 v[126:129], v[66:69], v[142:145], v[126:129]
	v_mfma_f32_16x16x32_bf16 v[126:129], v[60:63], v[146:149], v[126:129]
	v_mfma_f32_16x16x32_bf16 v[126:129], v[56:59], v[150:153], v[126:129]
	s_nop 7
	v_pk_mul_f32 v[128:129], v[166:167], v[128:129]
	v_pk_mul_f32 v[126:127], v[162:163], v[126:127]
	v_pk_fma_f32 v[124:125], v[170:171], v[124:125], v[128:129]
	v_pk_fma_f32 v[122:123], v[164:165], v[122:123], v[126:127]
	s_nop 0
	v_cvt_pk_bf16_f32 v122, v122, v123
	v_cvt_pk_bf16_f32 v123, v124, v125
	global_store_dwordx2 v[184:185], v[122:123], off offset:96
	ds_read_b64_tr_b16 v[134:135], v169 offset:34816
	ds_read_b64_tr_b16 v[136:137], v169 offset:39168
	ds_read_b64_tr_b16 v[130:131], v157 offset:34816
	ds_read_b64_tr_b16 v[132:133], v157 offset:39168
	ds_read_b64_tr_b16 v[126:127], v155 offset:34816
	ds_read_b64_tr_b16 v[128:129], v155 offset:39168
	ds_read_b64_tr_b16 v[122:123], v64 offset:34816
	ds_read_b64_tr_b16 v[124:125], v64 offset:39168
	s_waitcnt lgkmcnt(6)
	v_mfma_f32_16x16x32_bf16 v[12:15], v[106:109], v[134:137], v[12:15]
	v_mfma_f32_16x16x32_bf16 v[4:7], v[90:93], v[134:137], v[4:7]
	v_mfma_f32_16x16x32_bf16 v[0:3], v[74:77], v[134:137], v[0:3]
	v_mfma_f32_16x16x32_bf16 v[8:11], v[70:73], v[134:137], v[8:11]
	s_waitcnt lgkmcnt(4)
	v_mfma_f32_16x16x32_bf16 v[12:15], v[110:113], v[130:133], v[12:15]
	v_mfma_f32_16x16x32_bf16 v[4:7], v[94:97], v[130:133], v[4:7]
	v_mfma_f32_16x16x32_bf16 v[0:3], v[78:81], v[130:133], v[0:3]
	v_mfma_f32_16x16x32_bf16 v[8:11], v[66:69], v[130:133], v[8:11]
	s_waitcnt lgkmcnt(2)
	v_mfma_f32_16x16x32_bf16 v[12:15], v[114:117], v[126:129], v[12:15]
	v_mfma_f32_16x16x32_bf16 v[4:7], v[98:101], v[126:129], v[4:7]
	v_mfma_f32_16x16x32_bf16 v[0:3], v[82:85], v[126:129], v[0:3]
	v_mfma_f32_16x16x32_bf16 v[8:11], v[60:63], v[126:129], v[8:11]
	s_waitcnt lgkmcnt(0)
	v_mfma_f32_16x16x32_bf16 v[12:15], v[118:121], v[122:125], v[12:15]
	v_mfma_f32_16x16x32_bf16 v[4:7], v[102:105], v[122:125], v[4:7]
	v_mfma_f32_16x16x32_bf16 v[0:3], v[86:89], v[122:125], v[0:3]
	v_mfma_f32_16x16x32_bf16 v[8:11], v[56:59], v[122:125], v[8:11]
	s_cbranch_scc1 .LBB0_243
	s_barrier
	s_waitcnt vmcnt(8)
	ds_write_b128 v225, v[16:19]
	s_waitcnt vmcnt(7)
	ds_write_b128 v225, v[20:23] offset:34816
	s_waitcnt vmcnt(6)
	ds_write_b128 v223, v[24:27]
	s_waitcnt vmcnt(5)
	ds_write_b128 v223, v[28:31] offset:34816
	ds_write_b128 v221, v[36:39]
	ds_write_b128 v221, v[40:43] offset:34816
	ds_write_b128 v220, v[44:47]
	ds_write_b128 v220, v[48:51] offset:34816
	v_lshlrev_b32_e32 v16, 16, v52
	v_and_b32_e32 v17, 0xffff0000, v52
	v_lshlrev_b32_e32 v18, 16, v53
	v_and_b32_e32 v19, 0xffff0000, v53
	v_pk_mul_f32 v[16:17], v[182:183], v[16:17]
	v_pk_mul_f32 v[18:19], v[182:183], v[18:19]
	v_cvt_pk_bf16_f32 v16, v16, v17
	v_cvt_pk_bf16_f32 v17, v18, v19
	v_lshlrev_b32_e32 v18, 16, v54
	v_and_b32_e32 v19, 0xffff0000, v54
	v_lshlrev_b32_e32 v20, 16, v55
	v_and_b32_e32 v21, 0xffff0000, v55
	v_pk_mul_f32 v[18:19], v[182:183], v[18:19]
	v_pk_mul_f32 v[20:21], v[182:183], v[20:21]
	v_cvt_pk_bf16_f32 v18, v18, v19
	v_cvt_pk_bf16_f32 v19, v20, v21
	ds_write_b128 v211, v[16:19]
	s_waitcnt vmcnt(4)
	v_lshlrev_b32_e32 v16, 16, v32
	v_and_b32_e32 v17, 0xffff0000, v32
	v_lshlrev_b32_e32 v18, 16, v33
	v_and_b32_e32 v19, 0xffff0000, v33
	v_pk_mul_f32 v[16:17], v[180:181], v[16:17]
	v_pk_mul_f32 v[18:19], v[180:181], v[18:19]
	v_cvt_pk_bf16_f32 v16, v16, v17
	v_cvt_pk_bf16_f32 v17, v18, v19
	v_lshlrev_b32_e32 v18, 16, v34
	v_and_b32_e32 v19, 0xffff0000, v34
	v_lshlrev_b32_e32 v20, 16, v35
	v_and_b32_e32 v21, 0xffff0000, v35
	v_pk_mul_f32 v[18:19], v[180:181], v[18:19]
	v_pk_mul_f32 v[20:21], v[180:181], v[20:21]
	v_cvt_pk_bf16_f32 v18, v18, v19
	v_cvt_pk_bf16_f32 v19, v20, v21
	ds_write_b128 v210, v[16:19]
	v_cvt_pk_bf16_f32 v16, v12, v13
	v_cvt_pk_bf16_f32 v17, v14, v15
	v_cvt_pk_bf16_f32 v18, v4, v5
	v_cvt_pk_bf16_f32 v19, v6, v7
	ds_write2_b64 v209, v[16:17], v[18:19] offset1:4
	v_cvt_pk_bf16_f32 v16, v0, v1
	v_cvt_pk_bf16_f32 v17, v2, v3
	v_cvt_pk_bf16_f32 v18, v8, v9
	v_cvt_pk_bf16_f32 v19, v10, v11
	ds_write2_b64 v209, v[16:17], v[18:19] offset0:8 offset1:12
	s_waitcnt lgkmcnt(0)
	s_barrier
; #define MFMA16(a, b, c) __builtin_amdgcn_mfma_f32_16x16x32_bf16((a), (b), (c), 0, 0, 0)
; __device__ __forceinline__ void mix_ret_prompt(const Params& p, LAS unsigned char* lds, int u) {
;     ...
;     bf16x8 Qf[4];
; #pragma unroll
;     for (int ks = 0; ks < 4; ++ks) Qf[ks] = ldfrag(Qi, irow, 32 * ks + 8 * fq, 272);
;     f32x4 sc8[8];
; #pragma unroll
;     for (int nt = 0; nt < 8; ++nt) {
;       sc8[nt] = (f32x4){0.f, 0.f, 0.f, 0.f};
; #pragma unroll
;       for (int ks = 0; ks < 4; ++ks) sc8[nt] = MFMA16(ldfrag(Ki, 16 * nt + fr, 32 * ks + 8 * fq, 272), Qf[ks], sc8[nt]);
; #pragma unroll
;       for (int j = 0; j < 4; ++j) if (16 * nt + 4 * fq + j > irow) sc8[nt][j] = 0.f;
;     }
	ds_read_b128 v[28:31], v208
	ds_read_b128 v[24:27], v208 offset:64
	ds_read_b128 v[20:23], v208 offset:128
	ds_read_b128 v[16:19], v208 offset:192
	ds_read_b128 v[32:35], v195 offset:34816
	ds_read_b128 v[36:39], v195 offset:34880
	ds_read_b128 v[40:43], v195 offset:39232
	s_waitcnt lgkmcnt(2)
	v_mfma_f32_16x16x32_bf16 v[32:35], v[32:35], v[28:31], 0
	v_add_u32_e32 v114, s34, v154
	v_add_u32_e32 v114, 0x780, v114
	v_ashrrev_i32_e32 v115, 31, v114
	s_waitcnt lgkmcnt(1)
	v_mfma_f32_16x16x32_bf16 v[32:35], v[36:39], v[24:27], v[32:35]
	ds_read_b128 v[36:39], v195 offset:34944
	v_lshlrev_b64 v[114:115], 12, v[114:115]
	v_lshl_add_u64 v[114:115], v[172:173], 0, v[114:115]
	s_waitcnt lgkmcnt(0)
	v_mfma_f32_16x16x32_bf16 v[32:35], v[36:39], v[20:23], v[32:35]
	ds_read_b128 v[36:39], v195 offset:35008
	v_pk_mul_f32 v[14:15], v[158:159], v[14:15]
	v_pk_mul_f32 v[12:13], v[160:161], v[12:13]
	s_waitcnt lgkmcnt(0)
	v_mfma_f32_16x16x32_bf16 v[32:35], v[36:39], v[16:19], v[32:35]
	v_mul_f32_e64 v6, v158, v6
	v_mul_f32_e64 v7, v159, v7
	v_pk_mul_f32 v[4:5], v[160:161], v[4:5]
	v_pk_mul_f32 v[2:3], v[158:159], v[2:3]
	s_nop 3
	v_cndmask_b32_e64 v36, v32, 0, s[92:93]
	v_cndmask_b32_e64 v32, v36, v32, s[90:91]
	ds_read_b128 v[36:39], v195 offset:39168
	s_waitcnt lgkmcnt(0)
	v_mfma_f32_16x16x32_bf16 v[36:39], v[36:39], v[28:31], 0
	v_cndmask_b32_e64 v33, 0, v33, s[90:91]
	v_cndmask_b32_e64 v34, v34, 0, s[94:95]
	v_cndmask_b32_e64 v35, v35, 0, s[96:97]
	v_mfma_f32_16x16x32_bf16 v[36:39], v[40:43], v[24:27], v[36:39]
	ds_read_b128 v[40:43], v195 offset:39296
	v_cvt_pk_bf16_f32 v110, v32, v33
	v_cvt_pk_bf16_f32 v111, v34, v35
	s_waitcnt lgkmcnt(0)
	v_mfma_f32_16x16x32_bf16 v[36:39], v[40:43], v[20:23], v[36:39]
	ds_read_b128 v[40:43], v195 offset:39360
	v_pk_mul_f32 v[0:1], v[160:161], v[0:1]
	v_pk_mul_f32 v[10:11], v[158:159], v[10:11]
	s_waitcnt lgkmcnt(0)
	v_mfma_f32_16x16x32_bf16 v[36:39], v[40:43], v[16:19], v[36:39]
	ds_read_b128 v[40:43], v195 offset:43584
	v_pk_mul_f32 v[8:9], v[160:161], v[8:9]
	v_readlane_b32 s30, v255, 50
	s_nop 4
	v_cndmask_b32_e64 v44, v36, 0, s[82:83]
	v_cndmask_b32_e64 v45, v37, 0, s[84:85]
	v_cndmask_b32_e64 v46, v38, 0, s[86:87]
	v_cndmask_b32_e64 v47, v39, 0, s[88:89]
	ds_read_b128 v[36:39], v195 offset:43520
	s_waitcnt lgkmcnt(0)
	v_mfma_f32_16x16x32_bf16 v[36:39], v[36:39], v[28:31], 0
	v_cvt_pk_bf16_f32 v112, v44, v45
	v_cvt_pk_bf16_f32 v113, v46, v47
	s_lshl_b32 s34, s30, 3
	v_mfma_f32_16x16x32_bf16 v[36:39], v[40:43], v[24:27], v[36:39]
	ds_read_b128 v[40:43], v195 offset:43648
	s_or_b32 s34, s34, s29
	s_ashr_i32 s35, s34, 31
	s_waitcnt lgkmcnt(0)
	v_mfma_f32_16x16x32_bf16 v[36:39], v[40:43], v[20:23], v[36:39]
	ds_read_b128 v[40:43], v195 offset:43712
	s_lshl_b64 s[34:35], s[34:35], 17
	v_readlane_b32 s29, v253, 7
	s_waitcnt lgkmcnt(0)
	v_mfma_f32_16x16x32_bf16 v[36:39], v[40:43], v[16:19], v[36:39]
	ds_read_b128 v[40:43], v195 offset:47936
	s_add_u32 s34, s29, s34
	v_readlane_b32 s29, v253, 8
	s_nop 4
	v_cndmask_b32_e64 v48, v36, 0, s[74:75]
	v_cndmask_b32_e64 v49, v37, 0, s[76:77]
	v_cndmask_b32_e64 v50, v38, 0, s[78:79]
	v_cndmask_b32_e64 v51, v39, 0, s[80:81]
	ds_read_b128 v[36:39], v195 offset:47872
	s_waitcnt lgkmcnt(0)
	v_mfma_f32_16x16x32_bf16 v[36:39], v[36:39], v[28:31], 0
	v_cvt_pk_bf16_f32 v106, v48, v49
	v_cvt_pk_bf16_f32 v107, v50, v51
	s_addc_u32 s35, s29, s35
	v_mfma_f32_16x16x32_bf16 v[36:39], v[40:43], v[24:27], v[36:39]
	ds_read_b128 v[40:43], v195 offset:48000
	v_readlane_b32 s29, v255, 51
	s_waitcnt lgkmcnt(0)
	v_mfma_f32_16x16x32_bf16 v[36:39], v[40:43], v[20:23], v[36:39]
	ds_read_b128 v[40:43], v195 offset:48064
	s_waitcnt lgkmcnt(0)
	v_mfma_f32_16x16x32_bf16 v[36:39], v[40:43], v[16:19], v[36:39]
	ds_read_b128 v[40:43], v195 offset:52288
	s_nop 6
	v_cndmask_b32_e64 v52, v36, 0, s[66:67]
	v_cndmask_b32_e64 v53, v37, 0, s[68:69]
	v_cndmask_b32_e64 v54, v38, 0, s[70:71]
	v_cndmask_b32_e64 v55, v39, 0, s[72:73]
	ds_read_b128 v[36:39], v195 offset:52224
	s_waitcnt lgkmcnt(0)
	v_mfma_f32_16x16x32_bf16 v[36:39], v[36:39], v[28:31], 0
	v_cvt_pk_bf16_f32 v108, v52, v53
	v_cvt_pk_bf16_f32 v109, v54, v55
	v_mfma_f32_16x16x32_bf16 v[36:39], v[40:43], v[24:27], v[36:39]
	ds_read_b128 v[40:43], v195 offset:52352
	s_waitcnt lgkmcnt(0)
	v_mfma_f32_16x16x32_bf16 v[36:39], v[40:43], v[20:23], v[36:39]
	ds_read_b128 v[40:43], v195 offset:52416
	s_waitcnt lgkmcnt(0)
	v_mfma_f32_16x16x32_bf16 v[36:39], v[40:43], v[16:19], v[36:39]
	ds_read_b128 v[40:43], v195 offset:56640
	s_nop 6
	v_cndmask_b32_e64 v56, v36, 0, s[58:59]
	v_cndmask_b32_e64 v57, v37, 0, s[60:61]
	v_cndmask_b32_e64 v58, v38, 0, s[62:63]
	v_cndmask_b32_e64 v59, v39, 0, s[64:65]
	ds_read_b128 v[36:39], v195 offset:56576
	s_waitcnt lgkmcnt(0)
	v_mfma_f32_16x16x32_bf16 v[36:39], v[36:39], v[28:31], 0
	v_cvt_pk_bf16_f32 v98, v56, v57
	v_cvt_pk_bf16_f32 v99, v58, v59
	v_readlane_b32 s64, v253, 3
	v_mfma_f32_16x16x32_bf16 v[36:39], v[40:43], v[24:27], v[36:39]
	ds_read_b128 v[40:43], v195 offset:56704
	v_readlane_b32 s65, v253, 4
	s_waitcnt lgkmcnt(0)
	v_mfma_f32_16x16x32_bf16 v[36:39], v[40:43], v[20:23], v[36:39]
	ds_read_b128 v[40:43], v195 offset:56768
	s_waitcnt lgkmcnt(0)
	v_mfma_f32_16x16x32_bf16 v[36:39], v[40:43], v[16:19], v[36:39]
	ds_read_b128 v[40:43], v195 offset:60992
	s_nop 6
	v_cndmask_b32_e64 v60, v36, 0, s[50:51]
	v_cndmask_b32_e64 v61, v37, 0, s[52:53]
	v_cndmask_b32_e64 v62, v38, 0, s[54:55]
	v_cndmask_b32_e64 v63, v39, 0, s[56:57]
	ds_read_b128 v[36:39], v195 offset:60928
	s_waitcnt lgkmcnt(0)
	v_mfma_f32_16x16x32_bf16 v[36:39], v[36:39], v[28:31], 0
	v_cvt_pk_bf16_f32 v100, v60, v61
	v_cvt_pk_bf16_f32 v101, v62, v63
	v_mfma_f32_16x16x32_bf16 v[36:39], v[40:43], v[24:27], v[36:39]
	ds_read_b128 v[40:43], v195 offset:61056
	s_waitcnt lgkmcnt(0)
; __device__ __forceinline__ u32x2 pack4(f32x4 v) { u32x2 r; r[0] = cvt_pk(v[0], v[1]); r[1] = cvt_pk(v[2], v[3]); return r; }
; #define MFMA16(a, b, c) __builtin_amdgcn_mfma_f32_16x16x32_bf16((a), (b), (c), 0, 0, 0)
; __device__ __forceinline__ void mix_ret_prompt(const Params& p, LAS unsigned char* lds, int u) {
;     ...
;     for (int nt = 0; nt < 8; ++nt) {
;       sc8[nt] = (f32x4){0.f, 0.f, 0.f, 0.f};
; #pragma unroll
;       for (int ks = 0; ks < 4; ++ks) sc8[nt] = MFMA16(ldfrag(Ki, 16 * nt + fr, 32 * ks + 8 * fq, 272), Qf[ks], sc8[nt]);
; #pragma unroll
;       for (int j = 0; j < 4; ++j) if (16 * nt + 4 * fq + j > irow) sc8[nt][j] = 0.f;
;     }
;     bf16x8 Pf[4];
; #pragma unroll
;     for (int k2 = 0; k2 < 4; ++k2) {
;       const u32x2 lo = pack4(sc8[2 * k2]), hi = pack4(sc8[2 * k2 + 1]);
;       const u32x4 t = (u32x4){lo[0], lo[1], hi[0], hi[1]};
;       Pf[k2] = __builtin_bit_cast(bf16x8, t);
;     }
;     bf16x8 Vf[4][4];
; #pragma unroll
;     for (int n = 0; n < 4; ++n)
; #pragma unroll
;       for (int k2 = 0; k2 < 4; ++k2) Vf[n][k2] = ldfrag_tr(Vi, 32 * k2 + 4 * fq, 32 * k2 + 16 + 4 * fq, 16 * n, 144, lane);
; #pragma unroll
;     for (int n = 0; n < 4; ++n) {
;       f32x4 aA = (f32x4){0.f, 0.f, 0.f, 0.f}, aB = (f32x4){0.f, 0.f, 0.f, 0.f};
; #pragma unroll
;       for (int k2 = 0; k2 < 4; ++k2) aA = MFMA16(Vf[n][k2], Pf[k2], aA);
; #pragma unroll
;       for (int ks = 0; ks < 4; ++ks) aB = MFMA16(ldfrag_tr(Si, 32 * ks + 8 * fq, 32 * ks + 8 * fq + 4, 16 * n, 144, lane), Qf[ks], aB);
;       const f32x4 o = aA * sa + aB * sb;
;       *(u32x2*)(RO + (size_t)(t0 + irow) * 2048 + h * 256 + es * 64 + 16 * n + 4 * fq) = pack4(o);
;     }
	v_mfma_f32_16x16x32_bf16 v[36:39], v[40:43], v[20:23], v[36:39]
	ds_read_b128 v[40:43], v195 offset:61120
	s_waitcnt lgkmcnt(0)
	v_mfma_f32_16x16x32_bf16 v[36:39], v[40:43], v[16:19], v[36:39]
	ds_read_b128 v[40:43], v195 offset:65344
	s_nop 6
	v_cndmask_b32_e64 v66, v36, 0, s[42:43]
	v_cndmask_b32_e64 v67, v37, 0, s[44:45]
	v_cndmask_b32_e64 v68, v38, 0, s[46:47]
	v_cndmask_b32_e64 v69, v39, 0, s[48:49]
	ds_read_b128 v[36:39], v195 offset:65280
	s_waitcnt lgkmcnt(0)
	v_mfma_f32_16x16x32_bf16 v[36:39], v[36:39], v[28:31], 0
	v_cvt_pk_bf16_f32 v102, v66, v67
	v_cvt_pk_bf16_f32 v103, v68, v69
	v_mfma_f32_16x16x32_bf16 v[36:39], v[40:43], v[24:27], v[36:39]
	ds_read_b128 v[40:43], v195 offset:65408
	s_waitcnt lgkmcnt(0)
	v_mfma_f32_16x16x32_bf16 v[36:39], v[40:43], v[20:23], v[36:39]
	ds_read_b128 v[40:43], v195 offset:65472
	s_waitcnt lgkmcnt(0)
	v_mfma_f32_16x16x32_bf16 v[36:39], v[40:43], v[16:19], v[36:39]
	s_nop 7
	v_cndmask_b32_e64 v36, v36, 0, vcc
	v_cndmask_b32_e64 v37, v37, 0, s[36:37]
	v_cndmask_b32_e64 v38, v38, 0, s[38:39]
	v_cndmask_b32_e64 v39, v39, 0, s[40:41]
	v_cvt_pk_bf16_f32 v104, v36, v37
	v_cvt_pk_bf16_f32 v105, v38, v39
	ds_read_b64_tr_b16 v[94:95], v194
	ds_read_b64_tr_b16 v[96:97], v194 offset:2304
	ds_read_b64_tr_b16 v[90:91], v193
	ds_read_b64_tr_b16 v[92:93], v193 offset:2304
	ds_read_b64_tr_b16 v[86:87], v192
	ds_read_b64_tr_b16 v[88:89], v192 offset:2304
	ds_read_b64_tr_b16 v[82:83], v191
	ds_read_b64_tr_b16 v[84:85], v191 offset:2304
	ds_read_b64_tr_b16 v[78:79], v196
	ds_read_b64_tr_b16 v[80:81], v196 offset:2304
	ds_read_b64_tr_b16 v[74:75], v197
	ds_read_b64_tr_b16 v[76:77], v197 offset:2304
	ds_read_b64_tr_b16 v[70:71], v198
	ds_read_b64_tr_b16 v[72:73], v198 offset:2304
	ds_read_b64_tr_b16 v[66:67], v199
	ds_read_b64_tr_b16 v[68:69], v199 offset:2304
	ds_read_b64_tr_b16 v[60:61], v200
	ds_read_b64_tr_b16 v[62:63], v200 offset:2304
	ds_read_b64_tr_b16 v[56:57], v201
	ds_read_b64_tr_b16 v[58:59], v201 offset:2304
	ds_read_b64_tr_b16 v[52:53], v202
	ds_read_b64_tr_b16 v[54:55], v202 offset:2304
	ds_read_b64_tr_b16 v[48:49], v203
	ds_read_b64_tr_b16 v[50:51], v203 offset:2304
	ds_read_b64_tr_b16 v[44:45], v204
	ds_read_b64_tr_b16 v[46:47], v204 offset:2304
	ds_read_b64_tr_b16 v[40:41], v205
	ds_read_b64_tr_b16 v[42:43], v205 offset:2304
	ds_read_b64_tr_b16 v[36:37], v206
	ds_read_b64_tr_b16 v[38:39], v206 offset:2304
	ds_read_b64_tr_b16 v[32:33], v207
	ds_read_b64_tr_b16 v[34:35], v207 offset:2304
	ds_read_b64_tr_b16 v[116:117], v190
	ds_read_b64_tr_b16 v[118:119], v190 offset:576
	ds_read_b64_tr_b16 v[120:121], v190 offset:4608
	ds_read_b64_tr_b16 v[122:123], v190 offset:5184
	s_waitcnt lgkmcnt(2)
	v_mfma_f32_16x16x32_bf16 v[116:119], v[116:119], v[28:31], 0
	s_waitcnt lgkmcnt(0)
	v_mfma_f32_16x16x32_bf16 v[116:119], v[120:123], v[24:27], v[116:119]
	ds_read_b64_tr_b16 v[120:121], v190 offset:9216
	ds_read_b64_tr_b16 v[122:123], v190 offset:9792
	s_waitcnt lgkmcnt(0)
	v_mfma_f32_16x16x32_bf16 v[116:119], v[120:123], v[20:23], v[116:119]
	ds_read_b64_tr_b16 v[120:121], v190 offset:13824
	ds_read_b64_tr_b16 v[122:123], v190 offset:14400
	s_waitcnt lgkmcnt(0)
	v_mfma_f32_16x16x32_bf16 v[116:119], v[120:123], v[16:19], v[116:119]
	v_mfma_f32_16x16x32_bf16 v[120:123], v[94:97], v[110:113], 0
	v_mfma_f32_16x16x32_bf16 v[120:123], v[90:93], v[106:109], v[120:123]
	v_mfma_f32_16x16x32_bf16 v[120:123], v[86:89], v[98:101], v[120:123]
	v_mfma_f32_16x16x32_bf16 v[120:123], v[82:85], v[102:105], v[120:123]
	s_nop 7
	v_pk_mul_f32 v[122:123], v[166:167], v[122:123]
	v_pk_mul_f32 v[120:121], v[162:163], v[120:121]
	v_pk_fma_f32 v[118:119], v[170:171], v[118:119], v[122:123]
	v_pk_fma_f32 v[116:117], v[164:165], v[116:117], v[120:121]
	s_nop 0
	v_cvt_pk_bf16_f32 v116, v116, v117
	v_cvt_pk_bf16_f32 v117, v118, v119
	global_store_dwordx2 v[114:115], v[116:117], off
	ds_read_b64_tr_b16 v[116:117], v243
	ds_read_b64_tr_b16 v[118:119], v243 offset:576
	ds_read_b64_tr_b16 v[120:121], v189 offset:4608
	ds_read_b64_tr_b16 v[122:123], v189 offset:5184
	s_waitcnt lgkmcnt(2)
	v_mfma_f32_16x16x32_bf16 v[116:119], v[116:119], v[28:31], 0
	s_waitcnt lgkmcnt(0)
	v_mfma_f32_16x16x32_bf16 v[116:119], v[120:123], v[24:27], v[116:119]
	ds_read_b64_tr_b16 v[120:121], v189 offset:9216
	ds_read_b64_tr_b16 v[122:123], v189 offset:9792
	s_waitcnt lgkmcnt(0)
	v_mfma_f32_16x16x32_bf16 v[116:119], v[120:123], v[20:23], v[116:119]
	ds_read_b64_tr_b16 v[120:121], v189 offset:13824
	ds_read_b64_tr_b16 v[122:123], v189 offset:14400
	s_waitcnt lgkmcnt(0)
	v_mfma_f32_16x16x32_bf16 v[116:119], v[120:123], v[16:19], v[116:119]
	v_mfma_f32_16x16x32_bf16 v[120:123], v[78:81], v[110:113], 0
	v_mfma_f32_16x16x32_bf16 v[120:123], v[74:77], v[106:109], v[120:123]
	v_mfma_f32_16x16x32_bf16 v[120:123], v[70:73], v[98:101], v[120:123]
	v_mfma_f32_16x16x32_bf16 v[120:123], v[66:69], v[102:105], v[120:123]
	s_nop 7
	v_pk_mul_f32 v[122:123], v[166:167], v[122:123]
	v_pk_mul_f32 v[120:121], v[162:163], v[120:121]
	v_pk_fma_f32 v[118:119], v[170:171], v[118:119], v[122:123]
	v_pk_fma_f32 v[116:117], v[164:165], v[116:117], v[120:121]
	s_nop 0
	v_cvt_pk_bf16_f32 v116, v116, v117
	v_cvt_pk_bf16_f32 v117, v118, v119
	global_store_dwordx2 v[114:115], v[116:117], off offset:32
	ds_read_b64_tr_b16 v[116:117], v244
	ds_read_b64_tr_b16 v[118:119], v244 offset:576
	ds_read_b64_tr_b16 v[120:121], v188 offset:4608
	ds_read_b64_tr_b16 v[122:123], v188 offset:5184
	s_waitcnt lgkmcnt(2)
; __device__ __forceinline__ u32x2 pack4(f32x4 v) { u32x2 r; r[0] = cvt_pk(v[0], v[1]); r[1] = cvt_pk(v[2], v[3]); return r; }
; #define MFMA16(a, b, c) __builtin_amdgcn_mfma_f32_16x16x32_bf16((a), (b), (c), 0, 0, 0)
; __device__ __forceinline__ void mix_ret_prompt(const Params& p, LAS unsigned char* lds, int u) {
;     ...
;     for (int n = 0; n < 4; ++n) {
;       f32x4 aA = (f32x4){0.f, 0.f, 0.f, 0.f}, aB = (f32x4){0.f, 0.f, 0.f, 0.f};
; #pragma unroll
;       for (int k2 = 0; k2 < 4; ++k2) aA = MFMA16(Vf[n][k2], Pf[k2], aA);
; #pragma unroll
;       for (int ks = 0; ks < 4; ++ks) aB = MFMA16(ldfrag_tr(Si, 32 * ks + 8 * fq, 32 * ks + 8 * fq + 4, 16 * n, 144, lane), Qf[ks], aB);
;       const f32x4 o = aA * sa + aB * sb;
;       *(u32x2*)(RO + (size_t)(t0 + irow) * 2048 + h * 256 + es * 64 + 16 * n + 4 * fq) = pack4(o);
;     }
;     bf16x8 Kt[4];
; #pragma unroll
;     for (int k2 = 0; k2 < 4; ++k2) Kt[k2] = ldfrag_tr(Ki, 32 * k2 + 4 * fq, 32 * k2 + 16 + 4 * fq, 16 * w, 272, lane);
; #pragma unroll
;     for (int n = 0; n < 4; ++n) {
;       accS[n] = accS[n] * cd;
; #pragma unroll
;       for (int k2 = 0; k2 < 4; ++k2) accS[n] = MFMA16(Vf[n][k2], Kt[k2], accS[n]);
;     }
;   }
;   float* so = p.out + O_SRP + ((size_t)(b * 8 + h) * 128 + irow) * 256 + es * 64;
; #pragma unroll
;   for (int n = 0; n < 4; ++n) *(f32x4*)(so + 16 * n + 4 * fq) = accS[n];
	v_mfma_f32_16x16x32_bf16 v[116:119], v[116:119], v[28:31], 0
	s_waitcnt lgkmcnt(0)
	v_mfma_f32_16x16x32_bf16 v[116:119], v[120:123], v[24:27], v[116:119]
	ds_read_b64_tr_b16 v[120:121], v188 offset:9216
	ds_read_b64_tr_b16 v[122:123], v188 offset:9792
	s_waitcnt lgkmcnt(0)
	v_mfma_f32_16x16x32_bf16 v[116:119], v[120:123], v[20:23], v[116:119]
	ds_read_b64_tr_b16 v[120:121], v188 offset:13824
	ds_read_b64_tr_b16 v[122:123], v188 offset:14400
	s_waitcnt lgkmcnt(0)
	v_mfma_f32_16x16x32_bf16 v[116:119], v[120:123], v[16:19], v[116:119]
	v_mfma_f32_16x16x32_bf16 v[120:123], v[60:63], v[110:113], 0
	v_mfma_f32_16x16x32_bf16 v[120:123], v[56:59], v[106:109], v[120:123]
	v_mfma_f32_16x16x32_bf16 v[120:123], v[52:55], v[98:101], v[120:123]
	v_mfma_f32_16x16x32_bf16 v[120:123], v[48:51], v[102:105], v[120:123]
	s_nop 7
	v_pk_mul_f32 v[122:123], v[166:167], v[122:123]
	v_pk_mul_f32 v[120:121], v[162:163], v[120:121]
	v_pk_fma_f32 v[118:119], v[170:171], v[118:119], v[122:123]
	v_pk_fma_f32 v[116:117], v[164:165], v[116:117], v[120:121]
	s_nop 0
	v_cvt_pk_bf16_f32 v116, v116, v117
	v_cvt_pk_bf16_f32 v117, v118, v119
	global_store_dwordx2 v[114:115], v[116:117], off offset:64
	ds_read_b64_tr_b16 v[116:117], v245
	ds_read_b64_tr_b16 v[118:119], v245 offset:576
	s_waitcnt lgkmcnt(0)
	v_mfma_f32_16x16x32_bf16 v[28:31], v[116:119], v[28:31], 0
	ds_read_b64_tr_b16 v[116:117], v187 offset:4608
	ds_read_b64_tr_b16 v[118:119], v187 offset:5184
	s_waitcnt lgkmcnt(0)
	v_mfma_f32_16x16x32_bf16 v[24:27], v[116:119], v[24:27], v[28:31]
	s_nop 3
	ds_read_b64_tr_b16 v[28:29], v187 offset:9216
	ds_read_b64_tr_b16 v[30:31], v187 offset:9792
	s_waitcnt lgkmcnt(0)
	v_mfma_f32_16x16x32_bf16 v[20:23], v[28:31], v[20:23], v[24:27]
	s_nop 2
	ds_read_b64_tr_b16 v[24:25], v187 offset:13824
	ds_read_b64_tr_b16 v[26:27], v187 offset:14400
	s_waitcnt lgkmcnt(0)
	v_mfma_f32_16x16x32_bf16 v[16:19], v[24:27], v[16:19], v[20:23]
	v_mfma_f32_16x16x32_bf16 v[20:23], v[44:47], v[110:113], 0
	v_mfma_f32_16x16x32_bf16 v[20:23], v[40:43], v[106:109], v[20:23]
	v_mfma_f32_16x16x32_bf16 v[20:23], v[36:39], v[98:101], v[20:23]
	v_mfma_f32_16x16x32_bf16 v[20:23], v[32:35], v[102:105], v[20:23]
	s_nop 7
	v_pk_mul_f32 v[22:23], v[166:167], v[22:23]
	v_pk_mul_f32 v[20:21], v[162:163], v[20:21]
	v_pk_fma_f32 v[18:19], v[170:171], v[18:19], v[22:23]
	v_pk_fma_f32 v[16:17], v[164:165], v[16:17], v[20:21]
	s_nop 0
	v_cvt_pk_bf16_f32 v16, v16, v17
	v_cvt_pk_bf16_f32 v17, v18, v19
	global_store_dwordx2 v[114:115], v[16:17], off offset:96
	ds_read_b64_tr_b16 v[16:17], v169 offset:34816
	ds_read_b64_tr_b16 v[18:19], v169 offset:39168
	ds_read_b64_tr_b16 v[20:21], v157 offset:34816
	ds_read_b64_tr_b16 v[22:23], v157 offset:39168
	ds_read_b64_tr_b16 v[24:25], v155 offset:34816
	ds_read_b64_tr_b16 v[26:27], v155 offset:39168
	ds_read_b64_tr_b16 v[28:29], v64 offset:34816
	ds_read_b64_tr_b16 v[30:31], v64 offset:39168
	s_waitcnt lgkmcnt(6)
	v_mfma_f32_16x16x32_bf16 v[12:15], v[94:97], v[16:19], v[12:15]
	v_ashrrev_i32_e32 v155, 31, v154
	v_lshlrev_b32_e32 v64, 2, v156
	v_mfma_f32_16x16x32_bf16 v[4:7], v[78:81], v[16:19], v[4:7]
	v_mfma_f32_16x16x32_bf16 v[0:3], v[60:63], v[16:19], v[0:3]
	v_mfma_f32_16x16x32_bf16 v[8:11], v[44:47], v[16:19], v[8:11]
	v_lshlrev_b64 v[16:17], 10, v[154:155]
	v_lshl_add_u64 v[16:17], s[34:35], 0, v[16:17]
	v_readlane_b32 s34, v255, 1
	s_waitcnt lgkmcnt(4)
	v_mfma_f32_16x16x32_bf16 v[12:15], v[90:93], v[20:23], v[12:15]
	v_readlane_b32 s35, v255, 2
	s_lshl_b32 s34, s29, 2
	s_mov_b32 s29, s35
	v_mfma_f32_16x16x32_bf16 v[4:7], v[74:77], v[20:23], v[4:7]
	v_writelane_b32 v255, s28, 1
	v_lshl_add_u64 v[16:17], v[16:17], 0, s[34:35]
	v_lshl_add_u64 v[16:17], v[16:17], 0, v[64:65]
	v_mfma_f32_16x16x32_bf16 v[0:3], v[56:59], v[20:23], v[0:3]
	v_writelane_b32 v255, s29, 2
	s_nop 0
	v_readlane_b32 s94, v255, 35
	v_mfma_f32_16x16x32_bf16 v[8:11], v[40:43], v[20:23], v[8:11]
	v_readlane_b32 s96, v255, 37
	v_readlane_b32 s90, v255, 29
	v_readlane_b32 s92, v255, 31
	s_waitcnt lgkmcnt(2)
	v_mfma_f32_16x16x32_bf16 v[12:15], v[86:89], v[24:27], v[12:15]
	v_readlane_b32 s95, v255, 36
	v_readlane_b32 s97, v255, 38
	v_readlane_b32 s91, v255, 30
	v_mfma_f32_16x16x32_bf16 v[4:7], v[70:73], v[24:27], v[4:7]
	v_mfma_f32_16x16x32_bf16 v[0:3], v[52:55], v[24:27], v[0:3]
	v_mfma_f32_16x16x32_bf16 v[8:11], v[36:39], v[24:27], v[8:11]
	s_waitcnt lgkmcnt(0)
	v_mfma_f32_16x16x32_bf16 v[12:15], v[82:85], v[28:31], v[12:15]
	v_mfma_f32_16x16x32_bf16 v[4:7], v[66:69], v[28:31], v[4:7]
	v_mfma_f32_16x16x32_bf16 v[0:3], v[48:51], v[28:31], v[0:3]
	v_mfma_f32_16x16x32_bf16 v[8:11], v[32:35], v[28:31], v[8:11]
	s_nop 4
	global_store_dwordx4 v[16:17], v[12:15], off
	global_store_dwordx4 v[16:17], v[4:7], off offset:64
	global_store_dwordx4 v[16:17], v[0:3], off offset:128
	global_store_dwordx4 v[16:17], v[8:11], off offset:192
	s_branch .LBB0_182
